# P2: windowed-item block placed at position 0/5/10/15 of each workgroup's 20-item sequence by bits 3-4 of blockIdx (4-way rotation instead of 2-way swap)
# baseline (speedup 1.0000x reference)
; __device__ __forceinline__ Item decode(int k, int na0, int nA, int nb0) {
;     Item I; int tok0;
;     if (k < nA) { const int ia = na0 + k; I.isA = 1; I.hs = ia / (TT / 128); tok0 = (ia % (TT / 128)) * 128; I.dil = 1; }
;     else { const int ib = nb0 + (k - nA); I.hs = ib / (TT / 256); I.isA = 0; const int gi = I.hs >> 2; tok0 = (ib % (TT / 256)) * 256; I.dil = gi == 0 ? 1 : (gi == 1 ? 4 : 16); }
;     int L;
;     if (tok0 < TP) { L = 2048; I.seq0 = (tok0 / 2048) * 2048; } else { L = 8192; I.seq0 = TP + ((tok0 - TP) / 8192) * 8192; }
;     I.res = 0; I.j0 = tok0 - I.seq0; I.Lr = L; I.Lre = L; I.pair = 0;
;     ...
;     const int na0 = (int)((long)bx * NITEM_A / G), nA = (int)((long)(bx + 1) * NITEM_A / G) - na0;
;     const int nb0 = (int)((long)bx * NITEM_B / G), nB = (int)((long)(bx + 1) * NITEM_B / G) - nb0;
;     const int nloc = nA + nB, r0 = tid >> 3, ch = tid & 7;
;     v4u pk[6], pv[6];
;     ...
;     if (nloc <= 0) return;
;     Item cur = decode(0, na0, nA, nb0), nxt = cur;
.LBB0_146:
	s_sub_i32 s3, s4, s12
	s_add_u32 s14, s20, 0x7800000
	s_addc_u32 s15, s21, 0
	s_sub_i32 s13, s8, s44
	s_add_i32 s13, s13, s3
	s_bfe_u32 s32, s2, 0x20003
	s_mul_i32 s32, s32, 5
	s_cmp_eq_u32 s32, 0
	s_cbranch_scc1 .Lmy_noswap
	s_mov_b32 s3, 0
	s_sub_i32 s12, s12, s32

; __device__ __forceinline__ Item decode(int k, int na0, int nA, int nb0) {
;     Item I; int tok0;
;     if (k < nA) { const int ia = na0 + k; I.isA = 1; I.hs = ia / (TT / 128); tok0 = (ia % (TT / 128)) * 128; I.dil = 1; }
;     else { const int ib = nb0 + (k - nA); I.hs = ib / (TT / 256); I.isA = 0; const int gi = I.hs >> 2; tok0 = (ib % (TT / 256)) * 256; I.dil = gi == 0 ? 1 : (gi == 1 ? 4 : 16); }
;     ...
;         const bool more = (k + 1 < nloc);
;         if (more) { nxt = decode(k + 1, na0, nA, nb0); ATT_ISSUE(nxt); }
.LBB0_209:
	s_andn2_b64 vcc, exec, s[58:59]
	s_mov_b32 s69, s97
	s_mov_b32 s86, s99
	s_mov_b32 s85, s98
	s_mov_b32 s68, s45
	s_mov_b32 s87, s92
	s_mov_b32 s67, s46
	s_mov_b32 s0, s65
	s_cbranch_vccnz .LBB0_238
	s_sub_i32 s0, s84, s32
	s_cmp_ge_u32 s0, 5
	s_cselect_b64 s[58:59], -1, 0
	s_mov_b64 s[60:61], -1
	s_and_b64 vcc, exec, s[58:59]
	s_cbranch_vccz .LBB0_220
	s_add_i32 s0, s32, 5
	s_cmp_ge_u32 s84, s0
	s_cselect_b32 s0, 5, 0
	s_sub_i32 s0, s84, s0
	s_add_i32 s0, s0, s44
	s_mul_hi_i32 s1, s0, 0x66666667
	s_lshr_b32 s60, s1, 31
	s_ashr_i32 s1, s1, 7
	s_add_i32 s67, s1, s60
	s_mul_i32 s1, s67, 0x140
	s_sub_i32 s0, s0, s1
	s_lshl_b32 s0, s0, 8
	s_and_b32 s1, s67, -4
	s_cmp_eq_u32 s1, 4
	s_cselect_b32 s1, 4, 16
	s_cmp_gt_u32 s67, 3
	s_cselect_b32 s68, s1, 1
	s_mov_b32 s70, 0
	s_cbranch_execz .LBB0_221
